# v12 + layer-0 chain fully panel-local: SGU items remapped to own row panel (stats computed once per chunk), 8-WG panel barrier after in-proj, SGU->out-proj barrier split around the pp GEMM
# speedup vs baseline: 1.0521x; 1.0082x over previous
; __device__ __forceinline__ unsigned xb_ld(unsigned* p)              { return __hip_atomic_load(p, __ATOMIC_RELAXED, __HIP_MEMORY_SCOPE_AGENT); }
; __device__ __forceinline__ unsigned xb_add(unsigned* p, unsigned v) { return __hip_atomic_fetch_add(p, v, __ATOMIC_RELAXED, __HIP_MEMORY_SCOPE_AGENT); }
; #define XB_SPIN(cond, bar) do { unsigned _sp = 0; while (cond) { __builtin_amdgcn_s_sleep(1); \
;     if ((++_sp & 255u) == 0u) { if (xb_ld(&(bar)[XB_TMO])) break; if (_sp > XB_SPIN_CAP) { atomicAdd(&(bar)[XB_TMO], 1u); break; } } } } while (0)
; __device__ __forceinline__ void xcd_barrier(const XcdBarrier& b) {
;     asm volatile("s_waitcnt vmcnt(0)" ::: "memory");
;     __syncthreads();
;     if (threadIdx.x == 0) {
;         unsigned* bar = b.bar;
;         __builtin_amdgcn_s_waitcnt(0);
;         unsigned nloc = b.st[0], nx = b.st[1];
;         if (nloc == 0u) { xcd_barrier_complete(bar, b.x, nloc, nx); b.st[0] = nloc; b.st[1] = nx; }
;         const unsigned old = xb_add(&bar[XB_XSUB(b.x)], 1u);
;         const unsigned gen = old / nloc;
;         if (old + 1u == (gen + 1u) * nloc) {
;             __builtin_amdgcn_fence(__ATOMIC_RELEASE, "agent");
;             asm volatile("s_waitcnt vmcnt(0)" ::: "memory");
;             const unsigned og = xb_add(&bar[XB_TOP], 1u);
;             const unsigned tg = og / nx;
;             if (og + 1u == (tg + 1u) * nx) xb_add(&bar[XB_TOPGEN], 1u);
;             else XB_SPIN(xb_ld(&bar[XB_TOPGEN]) == tg, bar);
;             __builtin_amdgcn_fence(__ATOMIC_ACQUIRE, "agent");
;             xb_add(&bar[XB_XGEN(b.x)], 1u);
;             asm volatile("s_waitcnt vmcnt(0)" ::: "memory");
;         } else {
;             XB_SPIN(xb_ld(&bar[XB_XGEN(b.x)]) == gen, bar);
;             __builtin_amdgcn_fence(__ATOMIC_ACQUIRE, "agent");
;             asm volatile("s_waitcnt vmcnt(0)" ::: "memory");
;         }
;     }
;     __syncthreads();
; }
.LBB0_182:
	s_cmp_gt_i32 s43, 2
	s_cselect_b64 s[4:5], -1, 0
	s_and_b64 s[0:1], s[0:1], s[4:5]
	s_andn2_b64 vcc, exec, s[0:1]
	s_cbranch_vccnz .LBB0_232
	s_waitcnt vmcnt(0)
	s_waitcnt vmcnt(0) lgkmcnt(0)
	s_barrier
	s_and_saveexec_b64 s[0:1], s[12:13]
	s_cbranch_execz .LBB0_231
	v_readfirstlane_b32 s99, v255
	s_bcnt1_i32_b32 s99, s99
	v_mov_b32_e32 v253, 0x2000c
	v_mov_b32_e32 v254, s99
	ds_write_b32 v253, v254
	s_cmp_eq_u32 s99, 1
	s_cbranch_scc1 .Lpc1_fast
	buffer_wbl2 sc1
	s_waitcnt vmcnt(0)
.Lpc1_fast:
	s_and_b32 s98, s2, 7
	s_lshl_b32 s98, s98, 2
	s_bfe_u32 s99, s2, 0x20003
	s_or_b32 s98, s98, s99
	s_lshl_b32 s98, s98, 6
	s_add_i32 s98, s98, 0xa400
	v_mov_b32_e32 v250, s98
	v_mov_b32_e32 v252, 1
	global_atomic_add v250, v252, s[54:55] offset:16
	s_mov_b32 s99, 0
.Lpc1_spin:
	global_load_dword v251, v250, s[54:55] offset:16 sc1
	s_waitcnt vmcnt(0)
	v_readfirstlane_b32 s98, v251
	s_cmp_ge_u32 s98, 8
	s_cbranch_scc1 .Lpc1_ok
	s_sleep 1
	s_add_u32 s99, s99, 1
	s_cmp_lt_u32 s99, 0x40000
	s_cbranch_scc1 .Lpc1_spin

; #define LAS __attribute__((address_space(3)))
; __device__ __forceinline__ void sgu_phase(LAS unsigned char* lds, const bf16_t* U, const bf16_t* GV, const bf16_t* SZ, const float* stats, const float* vg, const float* vb,
;                                           const bf16_t* wsb, const float* b_s, bf16_t* Y, int G, int bid) {
;     constexpr int VST = 272;
;     LAS unsigned char* vnT = lds;
;     LAS f32x2* rstat = (LAS f32x2*)(lds + 128 * VST);
;     const int tid = threadIdx.x, wid = tid >> 6, lane = tid & 63, fr = lane & 15, fq = lane >> 4;
;     const bool xmap = (G == 256);
;     for (int itl = bid; itl < 1024; itl += G) {
;         const int it = xmap ? ((bid & 7) * 128 + (bid >> 3) + 32 * (itl >> 8)) : itl;
;         const int ci = it >> 4, g = it & 15, row0 = ci * 128;
.LBB0_232:
	s_cmp_lt_i32 s42, 3
	s_cselect_b64 s[0:1], -1, 0
	s_and_b64 s[4:5], s[0:1], s[4:5]
	s_andn2_b64 vcc, exec, s[4:5]
	s_cbranch_vccnz .LBB0_241
	s_cmpk_gt_i32 s2, 0x3ff
	s_cbranch_scc1 .LBB0_240
	s_cmpk_eq_i32 s34, 0x100
	s_waitcnt vmcnt(0)
	v_add_u32_e32 v5, 0x200, v164
	s_cselect_b64 s[6:7], -1, 0
	s_lshl_b32 s0, s2, 7
	v_lshrrev_b32_e32 v6, 7, v5
	s_and_b32 s3, s0, 0x380
	s_ashr_i32 s0, s2, 3
	v_lshrrev_b32_e32 v50, 4, v5
	v_bitop3_b32 v6, v6, v164, 15 bitop3:0x78
	v_lshrrev_b32_e32 v5, 3, v5
	s_add_i32 s3, s3, s0
	s_and_b32 s3, s2, 7
	s_lshl_b32 s3, s3, 7
	s_bfe_u32 s0, s2, 0x20003
	s_lshl_b32 s0, s0, 5
	s_add_i32 s3, s3, s0
	s_lshr_b32 s0, s2, 5
	s_lshl_b32 s0, s0, 1
	s_add_i32 s3, s3, s0
	s_movk_i32 s0, 0x80
	v_lshlrev_b32_e32 v6, 4, v6
	v_and_b32_e32 v5, 14, v5
	v_and_b32_e32 v0, 15, v164
	v_cmp_gt_u32_e32 vcc, s0, v164
	v_lshrrev_b32_e32 v1, 2, v164
	s_movk_i32 s0, 0xf0
	v_add3_u32 v5, 0, v6, v5
	v_or_b32_e32 v6, 0x400, v164
	v_and_or_b32 v47, v1, s0, v0
	v_lshrrev_b32_e32 v1, 7, v164
	v_lshrrev_b32_e32 v52, 4, v6
	v_lshrrev_b32_e32 v6, 7, v6
	v_bitop3_b32 v2, v1, v164, 15 bitop3:0x78
	v_lshrrev_b32_e32 v3, 3, v164
	v_bitop3_b32 v6, v6, v164, 15 bitop3:0x78
	v_lshlrev_b32_e32 v2, 4, v2
	v_and_b32_e32 v3, 14, v3
	v_lshlrev_b32_e32 v6, 4, v6
	v_add3_u32 v2, 0, v2, v3
	v_add3_u32 v3, 0, v6, v3
	v_add_u32_e32 v6, 0x600, v164
	v_lshlrev_b32_e32 v32, 4, v0
	v_mov_b32_e32 v33, 0
	v_lshrrev_b32_e32 v7, 7, v6
	v_bfe_u32 v41, v164, 4, 2
	v_lshl_add_u64 v[34:35], s[10:11], 0, v[32:33]
	v_lshlrev_b32_e32 v32, 5, v0
	v_lshrrev_b32_e32 v54, 4, v6
	v_bitop3_b32 v7, v7, v164, 15 bitop3:0x78
	v_lshrrev_b32_e32 v6, 3, v6
	v_lshl_add_u64 v[36:37], s[22:23], 0, v[32:33]
	v_lshl_add_u64 v[38:39], s[24:25], 0, v[32:33]
	v_lshlrev_b32_e32 v7, 4, v7
	v_and_b32_e32 v6, 14, v6
	s_movk_i32 s0, 0x110
	v_lshlrev_b32_e32 v32, 4, v41
	v_bfe_u32 v48, v164, 3, 1
	v_mul_u32_u24_e32 v4, 0x880, v0
	v_add3_u32 v6, 0, v7, v6
	v_mad_u32_u24 v56, v0, s0, 0
	v_add_u32_e32 v64, 1, v1
	v_lshl_add_u64 v[0:1], s[40:41], 0, v[32:33]
	s_mov_b64 s[0:1], 0x3c80000
	s_mov_b32 s19, 0
	v_lshl_add_u32 v46, v164, 3, 0
	v_lshlrev_b32_e32 v40, 2, v41
	v_lshl_add_u32 v49, v214, 3, 0
	v_lshl_add_u32 v51, v50, 3, 0
	v_lshl_add_u32 v53, v52, 3, 0
	v_lshl_add_u32 v55, v54, 3, 0
	v_or_b32_e32 v57, 2, v48
	v_or_b32_e32 v58, 4, v48
	v_or_b32_e32 v59, 6, v48
	v_or_b32_e32 v60, 8, v48
	v_or_b32_e32 v61, 10, v48
	v_or_b32_e32 v62, 12, v48
	v_or_b32_e32 v63, 14, v48
	v_lshl_add_u64 v[42:43], v[0:1], 0, s[0:1]
	s_mov_b32 s22, 0x3a000000
	s_mov_b32 s23, 0x800000
	v_add_u32_e32 v65, v2, v4
	v_add_u32_e32 v66, v5, v4
	v_add_u32_e32 v67, v3, v4
	v_add_u32_e32 v68, v6, v4
	s_mov_b32 s26, s2
; __device__ __forceinline__ void sgu_phase(LAS unsigned char* lds, const bf16_t* U, const bf16_t* GV, const bf16_t* SZ, const float* stats, const float* vg, const float* vb,
;                                           const bf16_t* wsb, const float* b_s, bf16_t* Y, int G, int bid) {
;     ...
;     for (int itl = bid; itl < 1024; itl += G) {
;         const int it = xmap ? ((bid & 7) * 128 + (bid >> 3) + 32 * (itl >> 8)) : itl;
;         const int ci = it >> 4, g = it & 15, row0 = ci * 128;
;         __syncthreads();
;         if (tid < 128) {
;             const float* sp = stats + (size_t)(row0 + tid) * 64; float s = 0.f, ss = 0.f;
; #pragma unroll
;             for (int i = 0; i < 16; ++i) { const f32x4 q = *(const f32x4*)(sp + i * 4); s += q[0] + q[2]; ss += q[1] + q[3]; }
;             const float mean = s * (1.0f / DM), var = ss * (1.0f / DM) - mean * mean;
;             rstat[tid] = (f32x2){mean, rsqrtf(var + 1e-5f)};
;         }
;         __syncthreads();
.LBB0_235:
	s_lshr_b32 s0, s26, 8
	s_and_b32 s1, s0, 1
	s_lshr_b32 s0, s0, 1
	s_lshl_b32 s0, s0, 4
	s_add_i32 s0, s0, s1
	s_add_i32 s18, s3, s0
	s_lshl_b32 s0, s18, 3
	s_and_b32 s27, s0, 0xffffff80
	s_waitcnt lgkmcnt(0)
	s_barrier
	s_lshl_b32 s24, s18, 7
	s_and_b32 s36, s24, 0x780
	s_mov_b32 s25, 0
	v_add_u32_e32 v240, s27, v47
	v_ashrrev_i32_e32 v241, 31, v240
	v_lshlrev_b64 v[240:241], 11, v[240:241]
	v_or3_b32 v240, v240, v40, s36
	v_lshlrev_b64 v[240:241], 1, v[240:241]
	v_lshl_add_u64 v[240:241], s[8:9], 0, v[240:241]
	v_add_lshl_u32 v242, s36, v47, 2
	global_load_dword v126, v242, s[28:29]
	global_load_dwordx2 v[110:111], v[240:241], off
	global_load_dwordx2 v[112:113], v[240:241], off offset:32
	global_load_dwordx2 v[114:115], v[240:241], off offset:64
	global_load_dwordx2 v[116:117], v[240:241], off offset:96
	global_load_dwordx2 v[118:119], v[240:241], off offset:128
	global_load_dwordx2 v[120:121], v[240:241], off offset:160
	global_load_dwordx2 v[122:123], v[240:241], off offset:192
	global_load_dwordx2 v[124:125], v[240:241], off offset:224
	s_lshl_b32 s24, s36, 1
	v_lshl_add_u64 v[236:237], v[34:35], 0, s[24:25]
	s_lshl_b32 s24, s36, 2
	v_lshl_add_u64 v[244:245], v[38:39], 0, s[24:25]
	v_lshl_add_u64 v[246:247], v[36:37], 0, s[24:25]
	v_or_b32_e32 v238, s27, v214
	v_ashrrev_i32_e32 v239, 31, v238
	v_lshlrev_b64 v[238:239], 12, v[238:239]
	v_lshl_add_u64 v[238:239], v[236:237], 0, v[238:239]
	global_load_dwordx4 v[130:133], v[238:239], off
	global_load_dwordx4 v[134:137], v[244:245], off
	global_load_dwordx4 v[138:141], v[246:247], off
	global_load_dwordx4 v[142:145], v[246:247], off offset:16
	global_load_dwordx4 v[146:149], v[244:245], off offset:16
	v_or_b32_e32 v238, s27, v50
	v_ashrrev_i32_e32 v239, 31, v238
	v_lshlrev_b64 v[238:239], 12, v[238:239]
	v_lshl_add_u64 v[238:239], v[236:237], 0, v[238:239]
	global_load_dwordx4 v[170:173], v[238:239], off
	global_load_dwordx4 v[174:177], v[244:245], off
	global_load_dwordx4 v[178:181], v[246:247], off
	global_load_dwordx4 v[182:185], v[246:247], off offset:16
	global_load_dwordx4 v[186:189], v[244:245], off offset:16
	v_or_b32_e32 v238, s27, v52
	v_ashrrev_i32_e32 v239, 31, v238
	v_lshlrev_b64 v[238:239], 12, v[238:239]
	v_lshl_add_u64 v[238:239], v[236:237], 0, v[238:239]
	global_load_dwordx4 v[190:193], v[238:239], off
	global_load_dwordx4 v[194:197], v[244:245], off
	global_load_dwordx4 v[198:201], v[246:247], off
	global_load_dwordx4 v[202:205], v[246:247], off offset:16
	global_load_dwordx4 v[206:209], v[244:245], off offset:16
	v_add_u32_e32 v238, s27, v54
	v_ashrrev_i32_e32 v239, 31, v238
	v_lshlrev_b64 v[238:239], 12, v[238:239]
	v_lshl_add_u64 v[238:239], v[236:237], 0, v[238:239]
	global_load_dwordx4 v[216:219], v[238:239], off
	global_load_dwordx4 v[220:223], v[244:245], off
	global_load_dwordx4 v[224:227], v[246:247], off
	global_load_dwordx4 v[228:231], v[246:247], off offset:16
	global_load_dwordx4 v[232:235], v[244:245], off offset:16
	s_and_saveexec_b64 s[24:25], vcc
	s_bitcmp1_b32 s26, 8
	s_cbranch_scc1 .LBB0_237
	s_cbranch_execz .LBB0_237
	v_or_b32_e32 v0, s27, v164
	v_ashrrev_i32_e32 v1, 31, v0
	v_lshlrev_b64 v[0:1], 8, v[0:1]
	v_lshl_add_u64 v[44:45], s[16:17], 0, v[0:1]
	global_load_dwordx4 v[0:3], v[44:45], off
	global_load_dwordx4 v[4:7], v[44:45], off offset:16
	global_load_dwordx4 v[8:11], v[44:45], off offset:32
	global_load_dwordx4 v[12:15], v[44:45], off offset:48
	global_load_dwordx4 v[16:19], v[44:45], off offset:64
	global_load_dwordx4 v[20:23], v[44:45], off offset:80
	global_load_dwordx4 v[24:27], v[44:45], off offset:96
	global_load_dwordx4 v[28:31], v[44:45], off offset:112
	global_load_dwordx4 v[70:73], v[44:45], off offset:128
	global_load_dwordx4 v[74:77], v[44:45], off offset:144
	global_load_dwordx4 v[78:81], v[44:45], off offset:160
	global_load_dwordx4 v[82:85], v[44:45], off offset:176
	global_load_dwordx4 v[86:89], v[44:45], off offset:192
	global_load_dwordx4 v[90:93], v[44:45], off offset:208
	global_load_dwordx4 v[94:97], v[44:45], off offset:224
	global_load_dwordx4 v[98:101], v[44:45], off offset:240
	s_waitcnt vmcnt(15)
	v_pk_add_f32 v[0:1], v[0:1], v[2:3]
	s_waitcnt vmcnt(14)
	v_pk_add_f32 v[2:3], v[4:5], v[6:7]
	v_pk_add_f32 v[0:1], v[0:1], 0 op_sel_hi:[1,0]
	s_waitcnt vmcnt(13)
	v_pk_add_f32 v[4:5], v[8:9], v[10:11]
	v_pk_add_f32 v[0:1], v[0:1], v[2:3]
	s_waitcnt vmcnt(12)
	v_pk_add_f32 v[6:7], v[12:13], v[14:15]
	v_pk_add_f32 v[0:1], v[0:1], v[4:5]
	s_waitcnt vmcnt(11)
	v_pk_add_f32 v[8:9], v[16:17], v[18:19]
	v_pk_add_f32 v[0:1], v[0:1], v[6:7]
	s_waitcnt vmcnt(10)
	v_pk_add_f32 v[10:11], v[20:21], v[22:23]
	v_pk_add_f32 v[0:1], v[0:1], v[8:9]
	s_waitcnt vmcnt(9)
	v_pk_add_f32 v[12:13], v[24:25], v[26:27]
	v_pk_add_f32 v[0:1], v[0:1], v[10:11]
	s_waitcnt vmcnt(8)
	v_pk_add_f32 v[14:15], v[28:29], v[30:31]
	v_pk_add_f32 v[0:1], v[0:1], v[12:13]
	s_waitcnt vmcnt(7)
	v_pk_add_f32 v[16:17], v[70:71], v[72:73]
	v_pk_add_f32 v[0:1], v[0:1], v[14:15]
	s_waitcnt vmcnt(6)
	v_pk_add_f32 v[18:19], v[74:75], v[76:77]
	v_pk_add_f32 v[0:1], v[0:1], v[16:17]
	s_waitcnt vmcnt(5)
	v_pk_add_f32 v[20:21], v[78:79], v[80:81]
	v_pk_add_f32 v[0:1], v[0:1], v[18:19]
	s_waitcnt vmcnt(4)
	v_pk_add_f32 v[22:23], v[82:83], v[84:85]
	v_pk_add_f32 v[0:1], v[0:1], v[20:21]
	s_waitcnt vmcnt(3)
	v_pk_add_f32 v[24:25], v[86:87], v[88:89]
	v_pk_add_f32 v[0:1], v[0:1], v[22:23]
	s_waitcnt vmcnt(2)
	v_pk_add_f32 v[26:27], v[90:91], v[92:93]
	v_pk_add_f32 v[0:1], v[0:1], v[24:25]
	s_waitcnt vmcnt(1)
	v_pk_add_f32 v[28:29], v[94:95], v[96:97]
	v_pk_add_f32 v[0:1], v[0:1], v[26:27]
	s_waitcnt vmcnt(0)
	v_pk_add_f32 v[30:31], v[98:99], v[100:101]
	v_pk_add_f32 v[0:1], v[0:1], v[28:29]
	s_nop 0
	v_pk_add_f32 v[0:1], v[0:1], v[30:31]
	s_nop 0
	v_pk_mul_f32 v[0:1], v[0:1], s[22:23] op_sel_hi:[1,0]
	s_nop 0
	v_fma_f32 v1, -v0, v0, v1
	v_add_f32_e32 v1, 0x3727c5ac, v1
	v_mul_f32_e32 v2, 0x4b800000, v1
	v_cmp_gt_f32_e64 s[0:1], s23, v1
	s_nop 1
	v_cndmask_b32_e64 v1, v1, v2, s[0:1]
	v_rsq_f32_e32 v1, v1
	s_nop 0
	v_mul_f32_e32 v2, 0x45800000, v1
	v_cndmask_b32_e64 v1, v1, v2, s[0:1]
	ds_write_b64 v46, v[0:1] offset:34816

; __device__ __forceinline__ unsigned xb_ld(unsigned* p)              { return __hip_atomic_load(p, __ATOMIC_RELAXED, __HIP_MEMORY_SCOPE_AGENT); }
; __device__ __forceinline__ unsigned xb_add(unsigned* p, unsigned v) { return __hip_atomic_fetch_add(p, v, __ATOMIC_RELAXED, __HIP_MEMORY_SCOPE_AGENT); }
; #define XB_SPIN(cond, bar) do { unsigned _sp = 0; while (cond) { __builtin_amdgcn_s_sleep(1); \
;     if ((++_sp & 255u) == 0u) { if (xb_ld(&(bar)[XB_TMO])) break; if (_sp > XB_SPIN_CAP) { atomicAdd(&(bar)[XB_TMO], 1u); break; } } } } while (0)
; __device__ __forceinline__ void xcd_barrier(const XcdBarrier& b) {
;     asm volatile("s_waitcnt vmcnt(0)" ::: "memory");
;     __syncthreads();
;     if (threadIdx.x == 0) {
;         unsigned* bar = b.bar;
;         __builtin_amdgcn_s_waitcnt(0);
;         unsigned nloc = b.st[0], nx = b.st[1];
;         if (nloc == 0u) { xcd_barrier_complete(bar, b.x, nloc, nx); b.st[0] = nloc; b.st[1] = nx; }
;         const unsigned old = xb_add(&bar[XB_XSUB(b.x)], 1u);
;         const unsigned gen = old / nloc;
;         if (old + 1u == (gen + 1u) * nloc) {
;             __builtin_amdgcn_fence(__ATOMIC_RELEASE, "agent");
;             asm volatile("s_waitcnt vmcnt(0)" ::: "memory");
;             const unsigned og = xb_add(&bar[XB_TOP], 1u);
;             const unsigned tg = og / nx;
;             if (og + 1u == (tg + 1u) * nx) xb_add(&bar[XB_TOPGEN], 1u);
;             else XB_SPIN(xb_ld(&bar[XB_TOPGEN]) == tg, bar);
;             __builtin_amdgcn_fence(__ATOMIC_ACQUIRE, "agent");
;             xb_add(&bar[XB_XGEN(b.x)], 1u);
;             asm volatile("s_waitcnt vmcnt(0)" ::: "memory");
;         } else {
;             XB_SPIN(xb_ld(&bar[XB_XGEN(b.x)]) == gen, bar);
;             __builtin_amdgcn_fence(__ATOMIC_ACQUIRE, "agent");
;             asm volatile("s_waitcnt vmcnt(0)" ::: "memory");
;         }
;     }
;     __syncthreads();
; }
.LBB0_241:
	s_cmp_gt_i32 s43, 3
	s_cselect_b64 s[0:1], -1, 0
	s_and_b64 s[4:5], s[4:5], s[0:1]
	s_andn2_b64 vcc, exec, s[4:5]
	s_cbranch_vccnz .LBB0_291
	s_waitcnt vmcnt(0)
	s_waitcnt vmcnt(0) lgkmcnt(0)
	s_barrier
	s_and_saveexec_b64 s[4:5], s[12:13]
	s_cbranch_execz .LBB0_290
	v_mov_b32_e32 v253, 0x2000c
	ds_read_b32 v254, v253
	s_waitcnt lgkmcnt(0)
	v_readfirstlane_b32 s99, v254
	s_cmp_eq_u32 s99, 1
	s_cbranch_scc1 .Lpc2_fast
	buffer_wbl2 sc1
	s_waitcnt vmcnt(0)
.Lpc2_fast:
	s_and_b32 s98, s2, 7
	s_lshl_b32 s98, s98, 2
	s_bfe_u32 s99, s2, 0x20003
	s_or_b32 s98, s98, s99
	s_lshl_b32 s98, s98, 6
	s_add_i32 s98, s98, 0xa400
	v_mov_b32_e32 v250, s98
	v_mov_b32_e32 v252, 1
	global_atomic_add v250, v252, s[54:55] offset:20

; __global__ void __launch_bounds__(NTHREADS, 2) mk_fwd(Params P) {
;     ...
;         { pg8::Gemm g{Y1, WOUT0, MTOK, 2048, 2048, 1 << 30, 0}; pg8::StaticOrder S; S.init(MTOK, 2048, G, bid);
;           EpiResLn<true> E{SLOTA, X1B, P.ln_g, P.ln_b, ws, 0, 0}; pg8::gemm_phase(lds, g, S, E); }
.Lpc2_spin:
	global_load_dword v251, v250, s[54:55] offset:20 sc1
	s_waitcnt vmcnt(0)
	v_readfirstlane_b32 s98, v251
	s_cmp_ge_u32 s98, 8
	s_cbranch_scc1 .Lpc2_ok
	s_sleep 1
	s_add_u32 s99, s99, 1
	s_cmp_lt_u32 s99, 0x40000
	s_cbranch_scc1 .Lpc2_spin

;     __device__ bool next(int i, Unit& u) const {
;         const long L = (long)i * G + c; if (L >= nwg) return false;
;         int wgid = (int)L; { const int q = nwg / NXCD, r = nwg % NXCD, xcd = wgid % NXCD, off = wgid / NXCD; wgid = (xcd < r ? xcd * (q + 1) : r * (q + 1) + (xcd - r) * q) + off; }
;         const int nig = WGM * nN, gid = wgid / nig, fm = gid * WGM, gsz = (nM - fm) < WGM ? (nM - fm) : WGM;
;         u.pm = fm + ((wgid % nig) % gsz); u.pn = (wgid % nig) / gsz; return true;
; __global__ void __launch_bounds__(NTHREADS, 2) mk_fwd(Params P) {
;     ...
;         { pg8::Gemm g{Y1, WOUT0, MTOK, 2048, 2048, 1 << 30, 0}; pg8::StaticOrder S; S.init(MTOK, 2048, G, bid);
;           EpiResLn<true> E{SLOTA, X1B, P.ln_g, P.ln_b, ws, 0, 0}; pg8::gemm_phase(lds, g, S, E); }
.Lpc2_done:
	s_or_b64 exec, exec, s[100:101]
	s_barrier
	s_cmpk_gt_i32 s2, 0xff
	v_readfirstlane_b32 s3, v164
	s_cbranch_scc1 .LBB0_366
	s_ashr_i32 s66, s2, 31
	s_lshr_b32 s0, s66, 29
	s_add_i32 s4, s2, s0
	s_and_b32 s0, s4, -8
	s_sub_i32 s5, s2, s0
	s_cmp_gt_i32 s5, -1
	s_cbranch_scc0 .LBB0_313
	s_lshl_b32 s6, s5, 5
	s_cbranch_execz .LBB0_314
	s_branch .LBB0_315
